# strategy 2 (prologue de-serialisation) x3: attention mask loads issued together; S5 y-constant fragment loads issued together; the 16 per-k gain values of the w_in / w_up conversion items loaded in on
# speedup vs baseline: 1.0130x; 1.0019x over previous
.LBB0_52:
	s_or_b64 exec, exec, s[2:3]
	v_cndmask_b32_e64 v2, 0, 1, s[4:5]
	v_cmp_ne_u32_e64 s[2:3], 1, v2
	s_andn2_b64 vcc, exec, s[4:5]
	s_cbranch_vccnz .LBB0_75
	s_load_dwordx16 s[36:51], s[0:1], 0x40
	v_ashrrev_i32_e32 v71, 31, v70
	s_ashr_i32 s11, s10, 31
	s_waitcnt lgkmcnt(0)
	v_lshl_add_u64 v[4:5], v[70:71], 2, s[38:39]
	global_load_dword v2, v[4:5], off
	v_lshl_add_u64 v[4:5], s[10:11], 0, v[74:75]
	v_lshl_add_u64 v[4:5], v[4:5], 2, s[38:39]
	global_load_dword v70, v[4:5], off offset:16
	global_load_dword v102, v[4:5], off offset:32
	global_load_dword v103, v[4:5], off offset:48
	global_load_dword v104, v[4:5], off offset:64
	global_load_dword v105, v[4:5], off offset:80
	global_load_dword v106, v[4:5], off offset:96
	global_load_dword v107, v[4:5], off offset:112
	global_load_dword v108, v[4:5], off offset:128
	global_load_dword v109, v[4:5], off offset:144
	global_load_dword v110, v[4:5], off offset:160
	global_load_dword v111, v[4:5], off offset:176
	global_load_dword v112, v[4:5], off offset:192
	global_load_dword v113, v[4:5], off offset:208
	global_load_dword v114, v[4:5], off offset:224
	global_load_dword v115, v[4:5], off offset:240
	s_waitcnt vmcnt(1)
	v_pk_mul_f32 v[4:5], v[64:65], v[2:3] op_sel_hi:[1,0]
	v_pk_mul_f32 v[78:79], v[62:63], v[2:3] op_sel_hi:[1,0]
	s_waitcnt vmcnt(0)
	v_pk_mul_f32 v[72:73], v[68:69], v[70:71] op_sel_hi:[1,0]
	v_pk_mul_f32 v[70:71], v[66:67], v[70:71] op_sel_hi:[1,0]
	s_cbranch_execnz .LBB0_55

.LBB0_55:
	v_add_u32_e32 v2, 0x410, v82
	ds_write2_b32 v82, v78, v79 offset1:1
	ds_write2_b32 v82, v4, v5 offset0:2 offset1:3
	ds_write2_b32 v2, v70, v71 offset1:1
	v_add_u32_e32 v2, 0x418, v82
	s_and_b64 vcc, exec, s[2:3]
	ds_write2_b32 v2, v72, v73 offset1:1
	s_cbranch_vccnz .LBB0_76
	s_load_dwordx16 s[36:51], s[0:1], 0x40
	s_ashr_i32 s11, s10, 31
	v_lshl_add_u64 v[4:5], s[10:11], 0, v[74:75]
	s_waitcnt lgkmcnt(0)
	v_lshl_add_u64 v[4:5], v[4:5], 2, s[38:39]
	v_mov_b32_e32 v2, v102
	v_mov_b32_e32 v62, v103
	s_waitcnt vmcnt(1)
	v_pk_mul_f32 v[4:5], v[56:57], v[2:3] op_sel_hi:[1,0]
	v_pk_mul_f32 v[66:67], v[54:55], v[2:3] op_sel_hi:[1,0]
	s_waitcnt vmcnt(0)
	v_pk_mul_f32 v[64:65], v[60:61], v[62:63] op_sel_hi:[1,0]
	v_pk_mul_f32 v[62:63], v[58:59], v[62:63] op_sel_hi:[1,0]
	s_cbranch_execnz .LBB0_58

.LBB0_58:
	v_add_u32_e32 v2, 0x820, v82
	s_waitcnt vmcnt(0)
	ds_write2_b32 v2, v66, v67 offset1:1
	v_add_u32_e32 v2, 0x828, v82
	ds_write2_b32 v2, v4, v5 offset1:1
	v_add_u32_e32 v2, 0xc30, v82
	ds_write2_b32 v2, v62, v63 offset1:1
	v_add_u32_e32 v2, 0xc38, v82
	s_and_b64 vcc, exec, s[2:3]
	ds_write2_b32 v2, v64, v65 offset1:1
	s_cbranch_vccnz .LBB0_77
	s_load_dwordx16 s[36:51], s[0:1], 0x40
	s_ashr_i32 s11, s10, 31
	v_lshl_add_u64 v[4:5], s[10:11], 0, v[74:75]
	s_waitcnt lgkmcnt(0)
	v_lshl_add_u64 v[4:5], v[4:5], 2, s[38:39]
	v_mov_b32_e32 v2, v104
	v_mov_b32_e32 v54, v105
	s_waitcnt vmcnt(1)
	v_pk_mul_f32 v[4:5], v[48:49], v[2:3] op_sel_hi:[1,0]
	v_pk_mul_f32 v[58:59], v[46:47], v[2:3] op_sel_hi:[1,0]
	s_waitcnt vmcnt(0)
	v_pk_mul_f32 v[56:57], v[52:53], v[54:55] op_sel_hi:[1,0]
	v_pk_mul_f32 v[54:55], v[50:51], v[54:55] op_sel_hi:[1,0]
	s_cbranch_execnz .LBB0_61

.LBB0_61:
	v_add_u32_e32 v2, 0x1040, v82
	ds_write2_b32 v2, v58, v59 offset1:1
	v_add_u32_e32 v2, 0x1048, v82
	ds_write2_b32 v2, v4, v5 offset1:1
	v_add_u32_e32 v2, 0x1450, v82
	ds_write2_b32 v2, v54, v55 offset1:1
	v_add_u32_e32 v2, 0x1458, v82
	s_and_b64 vcc, exec, s[2:3]
	ds_write2_b32 v2, v56, v57 offset1:1
	s_cbranch_vccnz .LBB0_78
	s_load_dwordx16 s[36:51], s[0:1], 0x40
	s_ashr_i32 s11, s10, 31
	v_lshl_add_u64 v[4:5], s[10:11], 0, v[74:75]
	s_waitcnt lgkmcnt(0)
	v_lshl_add_u64 v[4:5], v[4:5], 2, s[38:39]
	v_mov_b32_e32 v2, v106
	v_mov_b32_e32 v46, v107
	s_waitcnt vmcnt(1)
	v_pk_mul_f32 v[4:5], v[40:41], v[2:3] op_sel_hi:[1,0]
	v_pk_mul_f32 v[50:51], v[38:39], v[2:3] op_sel_hi:[1,0]
	s_waitcnt vmcnt(0)
	v_pk_mul_f32 v[48:49], v[44:45], v[46:47] op_sel_hi:[1,0]
	v_pk_mul_f32 v[46:47], v[42:43], v[46:47] op_sel_hi:[1,0]
	s_cbranch_execnz .LBB0_64

.LBB0_64:
	v_add_u32_e32 v2, 0x1860, v82
	ds_write2_b32 v2, v50, v51 offset1:1
	v_add_u32_e32 v2, 0x1868, v82
	ds_write2_b32 v2, v4, v5 offset1:1
	v_add_u32_e32 v2, 0x1c70, v82
	ds_write2_b32 v2, v46, v47 offset1:1
	v_add_u32_e32 v2, 0x1c78, v82
	s_and_b64 vcc, exec, s[2:3]
	ds_write2_b32 v2, v48, v49 offset1:1
	s_cbranch_vccnz .LBB0_79
	s_load_dwordx16 s[36:51], s[0:1], 0x40
	s_ashr_i32 s11, s10, 31
	v_lshl_add_u64 v[4:5], s[10:11], 0, v[74:75]
	s_waitcnt lgkmcnt(0)
	v_lshl_add_u64 v[4:5], v[4:5], 2, s[38:39]
	v_mov_b32_e32 v2, v108
	v_mov_b32_e32 v38, v109
	s_waitcnt vmcnt(1)
	v_pk_mul_f32 v[4:5], v[32:33], v[2:3] op_sel_hi:[1,0]
	v_pk_mul_f32 v[42:43], v[30:31], v[2:3] op_sel_hi:[1,0]
	s_waitcnt vmcnt(0)
	v_pk_mul_f32 v[40:41], v[36:37], v[38:39] op_sel_hi:[1,0]
	v_pk_mul_f32 v[38:39], v[34:35], v[38:39] op_sel_hi:[1,0]
	s_cbranch_execnz .LBB0_67

.LBB0_67:
	v_add_u32_e32 v2, 0x2080, v82
	ds_write2_b32 v2, v42, v43 offset1:1
	v_add_u32_e32 v2, 0x2088, v82
	ds_write2_b32 v2, v4, v5 offset1:1
	v_add_u32_e32 v2, 0x2490, v82
	ds_write2_b32 v2, v38, v39 offset1:1
	v_add_u32_e32 v2, 0x2498, v82
	s_and_b64 vcc, exec, s[2:3]
	ds_write2_b32 v2, v40, v41 offset1:1
	s_cbranch_vccnz .LBB0_80
	s_load_dwordx16 s[36:51], s[0:1], 0x40
	s_ashr_i32 s11, s10, 31
	v_lshl_add_u64 v[4:5], s[10:11], 0, v[74:75]
	s_waitcnt lgkmcnt(0)
	v_lshl_add_u64 v[4:5], v[4:5], 2, s[38:39]
	v_mov_b32_e32 v2, v110
	v_mov_b32_e32 v30, v111
	s_waitcnt vmcnt(1)
	v_pk_mul_f32 v[4:5], v[24:25], v[2:3] op_sel_hi:[1,0]
	v_pk_mul_f32 v[34:35], v[22:23], v[2:3] op_sel_hi:[1,0]
	s_waitcnt vmcnt(0)
	v_pk_mul_f32 v[32:33], v[28:29], v[30:31] op_sel_hi:[1,0]
	v_pk_mul_f32 v[30:31], v[26:27], v[30:31] op_sel_hi:[1,0]
	s_cbranch_execnz .LBB0_70

.LBB0_70:
	v_add_u32_e32 v2, 0x28a0, v82
	ds_write2_b32 v2, v34, v35 offset1:1
	v_add_u32_e32 v2, 0x28a8, v82
	ds_write2_b32 v2, v4, v5 offset1:1
	v_add_u32_e32 v2, 0x2cb0, v82
	ds_write2_b32 v2, v30, v31 offset1:1
	v_add_u32_e32 v2, 0x2cb8, v82
	s_and_b64 vcc, exec, s[2:3]
	ds_write2_b32 v2, v32, v33 offset1:1
	s_cbranch_vccnz .LBB0_81
	s_load_dwordx16 s[36:51], s[0:1], 0x40
	s_ashr_i32 s11, s10, 31
	v_lshl_add_u64 v[4:5], s[10:11], 0, v[74:75]
	s_waitcnt lgkmcnt(0)
	v_lshl_add_u64 v[4:5], v[4:5], 2, s[38:39]
	v_mov_b32_e32 v2, v112
	v_mov_b32_e32 v22, v113
	s_waitcnt vmcnt(1)
	v_pk_mul_f32 v[4:5], v[16:17], v[2:3] op_sel_hi:[1,0]
	v_pk_mul_f32 v[26:27], v[14:15], v[2:3] op_sel_hi:[1,0]
	s_waitcnt vmcnt(0)
	v_pk_mul_f32 v[24:25], v[20:21], v[22:23] op_sel_hi:[1,0]
	v_pk_mul_f32 v[22:23], v[18:19], v[22:23] op_sel_hi:[1,0]
	s_cbranch_execnz .LBB0_73

.LBB0_73:
	v_add_u32_e32 v2, 0x30c0, v82
	ds_write2_b32 v2, v26, v27 offset1:1
	v_add_u32_e32 v2, 0x30c8, v82
	ds_write2_b32 v2, v4, v5 offset1:1
	v_add_u32_e32 v2, 0x34d0, v82
	ds_write2_b32 v2, v22, v23 offset1:1
	v_add_u32_e32 v2, 0x34d8, v82
	s_and_b64 vcc, exec, s[2:3]
	ds_write2_b32 v2, v24, v25 offset1:1
	s_cbranch_vccnz .LBB0_82
	s_load_dwordx16 s[36:51], s[0:1], 0x40
	s_ashr_i32 s11, s10, 31
	v_lshl_add_u64 v[4:5], s[10:11], 0, v[74:75]
	s_waitcnt lgkmcnt(0)
	v_lshl_add_u64 v[4:5], v[4:5], 2, s[38:39]
	v_mov_b32_e32 v2, v114
	v_mov_b32_e32 v14, v115
	s_waitcnt vmcnt(1)
	v_pk_mul_f32 v[4:5], v[8:9], v[2:3] op_sel_hi:[1,0]
	v_pk_mul_f32 v[18:19], v[6:7], v[2:3] op_sel_hi:[1,0]
	s_waitcnt vmcnt(0)
	v_pk_mul_f32 v[16:17], v[12:13], v[14:15] op_sel_hi:[1,0]
	v_pk_mul_f32 v[14:15], v[10:11], v[14:15] op_sel_hi:[1,0]
	s_cbranch_execnz .LBB0_19
	s_branch .LBB0_18

.LBB0_306:
	s_cmpk_gt_i32 s31, 0x1ff
	s_mov_b64 s[0:1], -1
	s_cbranch_scc0 .LBB0_340
	s_cmpk_gt_u32 s31, 0x5ff
	s_cbranch_scc0 .LBB0_337
	s_cmpk_gt_u32 s31, 0x9ff
	s_cbranch_scc0 .LBB0_334
	s_add_i32 s0, s31, 0xf600
	s_and_b32 s1, s0, 0xffff
	s_mul_i32 s1, s1, 0xba2f
	s_lshr_b32 s1, s1, 23
	s_mul_i32 s2, s1, 0xb0
	s_sub_i32 s0, s0, s2
	s_lshl_b32 s20, s0, 6
	s_lshl_b32 s2, s1, 6
	s_and_b32 s1, s20, 0xc0
	s_cmpk_lt_u32 s1, 0x80
	s_cselect_b64 vcc, -1, 0
	s_lshl_b32 s0, s0, 5
	v_or_b32_e32 v2, s1, v85
	s_and_b32 s0, s0, 0x1f80
	v_or_b32_e32 v3, s0, v2
	s_addk_i32 s0, 0x1580
	v_add_u32_e32 v2, s0, v2
	v_cndmask_b32_e32 v2, v2, v3, vcc
	v_lshlrev_b32_e32 v70, 2, v2
	v_or_b32_e32 v66, s2, v84
	v_lshl_add_u64 v[2:3], s[50:51], 0, v[70:71]
	s_mov_b32 s0, 0xb000
	v_mad_u64_u32 v[4:5], s[0:1], v66, s0, v[2:3]
	v_mul_u32_u24_e32 v70, 0xb000, v66
	v_lshl_add_u64 v[2:3], v[2:3], 0, v[70:71]
	s_mov_b32 s0, 0x2c000
	v_add_co_u32_e32 v6, vcc, s0, v2
	s_mov_b32 s0, 0x84000
	s_nop 0
	v_addc_co_u32_e32 v7, vcc, 0, v3, vcc
	global_load_dwordx4 v[58:61], v[4:5], off
	global_load_dwordx4 v[62:65], v[6:7], off
	v_add_co_u32_e32 v4, vcc, s29, v2
	v_add_lshl_u32 v70, v84, s2, 2
	s_nop 0
	v_addc_co_u32_e32 v5, vcc, 0, v3, vcc
	v_add_co_u32_e32 v6, vcc, s0, v2
	s_mov_b32 s0, 0xdc000
	s_nop 0
	v_addc_co_u32_e32 v7, vcc, 0, v3, vcc
	global_load_dwordx4 v[50:53], v[4:5], off
	global_load_dwordx4 v[54:57], v[6:7], off
	v_add_co_u32_e32 v4, vcc, s30, v2
	s_nop 1
	v_addc_co_u32_e32 v5, vcc, 0, v3, vcc
	v_add_co_u32_e32 v6, vcc, s0, v2
	s_mov_b32 s0, 0x108000
	s_nop 0
	v_addc_co_u32_e32 v7, vcc, 0, v3, vcc
	global_load_dwordx4 v[42:45], v[4:5], off
	global_load_dwordx4 v[46:49], v[6:7], off
	v_add_co_u32_e32 v4, vcc, s0, v2
	s_mov_b32 s0, 0x134000
	s_nop 0
	v_addc_co_u32_e32 v5, vcc, 0, v3, vcc
	v_add_co_u32_e32 v6, vcc, s0, v2
	s_mov_b32 s0, 0x160000
	s_nop 0
	v_addc_co_u32_e32 v7, vcc, 0, v3, vcc
	global_load_dwordx4 v[34:37], v[4:5], off
	global_load_dwordx4 v[38:41], v[6:7], off
	v_add_co_u32_e32 v4, vcc, s0, v2
	s_mov_b32 s0, 0x18c000
	s_nop 0
	v_addc_co_u32_e32 v5, vcc, 0, v3, vcc
	v_add_co_u32_e32 v6, vcc, s0, v2
	s_mov_b32 s0, 0x1b8000
	s_nop 0
	v_addc_co_u32_e32 v7, vcc, 0, v3, vcc
	global_load_dwordx4 v[26:29], v[4:5], off
	global_load_dwordx4 v[30:33], v[6:7], off
	v_add_co_u32_e32 v4, vcc, s0, v2
	s_mov_b32 s0, 0x1e4000
	s_nop 0
	v_addc_co_u32_e32 v5, vcc, 0, v3, vcc
	v_add_co_u32_e32 v6, vcc, s0, v2
	s_mov_b32 s0, 0x210000
	s_nop 0
	v_addc_co_u32_e32 v7, vcc, 0, v3, vcc
	global_load_dwordx4 v[18:21], v[4:5], off
	global_load_dwordx4 v[22:25], v[6:7], off
	v_add_co_u32_e32 v4, vcc, s0, v2
	v_cmp_ne_u32_e64 s[0:1], 1, v96
	s_nop 0
	v_addc_co_u32_e32 v5, vcc, 0, v3, vcc
	v_add_co_u32_e32 v6, vcc, 0x23c000, v2
	s_nop 1
	v_addc_co_u32_e32 v7, vcc, 0, v3, vcc
	global_load_dwordx4 v[10:13], v[4:5], off
	global_load_dwordx4 v[14:17], v[6:7], off
	v_add_co_u32_e32 v4, vcc, 0x268000, v2
	s_nop 1
	v_addc_co_u32_e32 v5, vcc, 0, v3, vcc
	v_add_co_u32_e32 v6, vcc, 0x294000, v2
	s_nop 1
	v_addc_co_u32_e32 v7, vcc, 0, v3, vcc
	global_load_dwordx4 v[2:5], v[4:5], off
	s_nop 0
	global_load_dwordx4 v[6:9], v[6:7], off
	s_andn2_b64 vcc, exec, s[16:17]
	s_cbranch_vccnz .LBB0_373
	v_lshlrev_b32_e32 v66, 2, v66
	global_load_dword v66, v66, s[48:49]
	s_nop 0
	global_load_dword v98, v70, s[48:49] offset:16
	global_load_dword v102, v70, s[48:49] offset:32
	global_load_dword v103, v70, s[48:49] offset:48
	global_load_dword v104, v70, s[48:49] offset:64
	global_load_dword v105, v70, s[48:49] offset:80
	global_load_dword v106, v70, s[48:49] offset:96
	global_load_dword v107, v70, s[48:49] offset:112
	global_load_dword v108, v70, s[48:49] offset:128
	global_load_dword v109, v70, s[48:49] offset:144
	global_load_dword v110, v70, s[48:49] offset:160
	global_load_dword v111, v70, s[48:49] offset:176
	global_load_dword v112, v70, s[48:49] offset:192
	global_load_dword v113, v70, s[48:49] offset:208
	global_load_dword v114, v70, s[48:49] offset:224
	global_load_dword v115, v70, s[48:49] offset:240
	s_waitcnt vmcnt(0)
	v_pk_mul_f32 v[80:81], v[60:61], v[66:67] op_sel_hi:[1,0]
	v_pk_mul_f32 v[82:83], v[58:59], v[66:67] op_sel_hi:[1,0]
	v_pk_mul_f32 v[68:69], v[64:65], v[98:99] op_sel_hi:[1,0]
	v_pk_mul_f32 v[66:67], v[62:63], v[98:99] op_sel_hi:[1,0]
	s_cbranch_execnz .LBB0_312

.LBB0_312:
	s_waitcnt vmcnt(0)
	v_add_u32_e32 v58, 0x410, v97
	ds_write2_b32 v97, v82, v83 offset1:1
	ds_write2_b32 v97, v80, v81 offset0:2 offset1:3
	ds_write2_b32 v58, v66, v67 offset1:1
	v_add_u32_e32 v58, 0x418, v97
	s_and_b64 vcc, exec, s[0:1]
	ds_write2_b32 v58, v68, v69 offset1:1
	s_cbranch_vccnz .LBB0_374
	v_mov_b32_e32 v58, v102
	v_mov_b32_e32 v66, v103
	s_waitcnt vmcnt(1)
	v_pk_mul_f32 v[62:63], v[52:53], v[58:59] op_sel_hi:[1,0]
	v_pk_mul_f32 v[64:65], v[50:51], v[58:59] op_sel_hi:[1,0]
	s_waitcnt vmcnt(0)
	v_pk_mul_f32 v[60:61], v[56:57], v[66:67] op_sel_hi:[1,0]
	v_pk_mul_f32 v[58:59], v[54:55], v[66:67] op_sel_hi:[1,0]
	s_cbranch_execnz .LBB0_315

.LBB0_315:
	v_add_u32_e32 v50, 0x820, v97
	ds_write2_b32 v50, v64, v65 offset1:1
	v_add_u32_e32 v50, 0x828, v97
	ds_write2_b32 v50, v62, v63 offset1:1
	v_add_u32_e32 v50, 0xc30, v97
	ds_write2_b32 v50, v58, v59 offset1:1
	v_add_u32_e32 v50, 0xc38, v97
	s_and_b64 vcc, exec, s[0:1]
	ds_write2_b32 v50, v60, v61 offset1:1
	s_cbranch_vccnz .LBB0_375
	v_mov_b32_e32 v50, v104
	v_mov_b32_e32 v58, v105
	s_waitcnt vmcnt(1)
	v_pk_mul_f32 v[54:55], v[44:45], v[50:51] op_sel_hi:[1,0]
	v_pk_mul_f32 v[56:57], v[42:43], v[50:51] op_sel_hi:[1,0]
	s_waitcnt vmcnt(0)
	v_pk_mul_f32 v[52:53], v[48:49], v[58:59] op_sel_hi:[1,0]
	v_pk_mul_f32 v[50:51], v[46:47], v[58:59] op_sel_hi:[1,0]
	s_cbranch_execnz .LBB0_318

.LBB0_318:
	v_add_u32_e32 v42, 0x1040, v97
	ds_write2_b32 v42, v56, v57 offset1:1
	v_add_u32_e32 v42, 0x1048, v97
	ds_write2_b32 v42, v54, v55 offset1:1
	v_add_u32_e32 v42, 0x1450, v97
	ds_write2_b32 v42, v50, v51 offset1:1
	v_add_u32_e32 v42, 0x1458, v97
	s_and_b64 vcc, exec, s[0:1]
	ds_write2_b32 v42, v52, v53 offset1:1
	s_cbranch_vccnz .LBB0_376
	v_mov_b32_e32 v42, v106
	v_mov_b32_e32 v50, v107
	s_waitcnt vmcnt(1)
	v_pk_mul_f32 v[46:47], v[36:37], v[42:43] op_sel_hi:[1,0]
	v_pk_mul_f32 v[48:49], v[34:35], v[42:43] op_sel_hi:[1,0]
	s_waitcnt vmcnt(0)
	v_pk_mul_f32 v[44:45], v[40:41], v[50:51] op_sel_hi:[1,0]
	v_pk_mul_f32 v[42:43], v[38:39], v[50:51] op_sel_hi:[1,0]
	s_cbranch_execnz .LBB0_321

.LBB0_321:
	v_add_u32_e32 v34, 0x1860, v97
	ds_write2_b32 v34, v48, v49 offset1:1
	v_add_u32_e32 v34, 0x1868, v97
	ds_write2_b32 v34, v46, v47 offset1:1
	v_add_u32_e32 v34, 0x1c70, v97
	ds_write2_b32 v34, v42, v43 offset1:1
	v_add_u32_e32 v34, 0x1c78, v97
	s_and_b64 vcc, exec, s[0:1]
	ds_write2_b32 v34, v44, v45 offset1:1
	s_cbranch_vccnz .LBB0_377
	v_mov_b32_e32 v34, v108
	v_mov_b32_e32 v42, v109
	s_waitcnt vmcnt(1)
	v_pk_mul_f32 v[38:39], v[28:29], v[34:35] op_sel_hi:[1,0]
	v_pk_mul_f32 v[40:41], v[26:27], v[34:35] op_sel_hi:[1,0]
	s_waitcnt vmcnt(0)
	v_pk_mul_f32 v[36:37], v[32:33], v[42:43] op_sel_hi:[1,0]
	v_pk_mul_f32 v[34:35], v[30:31], v[42:43] op_sel_hi:[1,0]
	s_cbranch_execnz .LBB0_324

.LBB0_324:
	v_add_u32_e32 v26, 0x2080, v97
	ds_write2_b32 v26, v40, v41 offset1:1
	v_add_u32_e32 v26, 0x2088, v97
	ds_write2_b32 v26, v38, v39 offset1:1
	v_add_u32_e32 v26, 0x2490, v97
	ds_write2_b32 v26, v34, v35 offset1:1
	v_add_u32_e32 v26, 0x2498, v97
	s_and_b64 vcc, exec, s[0:1]
	ds_write2_b32 v26, v36, v37 offset1:1
	s_cbranch_vccnz .LBB0_378
	v_mov_b32_e32 v26, v110
	v_mov_b32_e32 v34, v111
	s_waitcnt vmcnt(1)
	v_pk_mul_f32 v[30:31], v[20:21], v[26:27] op_sel_hi:[1,0]
	v_pk_mul_f32 v[32:33], v[18:19], v[26:27] op_sel_hi:[1,0]
	s_waitcnt vmcnt(0)
	v_pk_mul_f32 v[28:29], v[24:25], v[34:35] op_sel_hi:[1,0]
	v_pk_mul_f32 v[26:27], v[22:23], v[34:35] op_sel_hi:[1,0]
	s_cbranch_execnz .LBB0_327

.LBB0_327:
	v_add_u32_e32 v18, 0x28a0, v97
	ds_write2_b32 v18, v32, v33 offset1:1
	v_add_u32_e32 v18, 0x28a8, v97
	ds_write2_b32 v18, v30, v31 offset1:1
	v_add_u32_e32 v18, 0x2cb0, v97
	ds_write2_b32 v18, v26, v27 offset1:1
	v_add_u32_e32 v18, 0x2cb8, v97
	s_and_b64 vcc, exec, s[0:1]
	ds_write2_b32 v18, v28, v29 offset1:1
	s_cbranch_vccnz .LBB0_379
	v_mov_b32_e32 v18, v112
	v_mov_b32_e32 v26, v113
	s_waitcnt vmcnt(1)
	v_pk_mul_f32 v[22:23], v[12:13], v[18:19] op_sel_hi:[1,0]
	v_pk_mul_f32 v[24:25], v[10:11], v[18:19] op_sel_hi:[1,0]
	s_waitcnt vmcnt(0)
	v_pk_mul_f32 v[20:21], v[16:17], v[26:27] op_sel_hi:[1,0]
	v_pk_mul_f32 v[18:19], v[14:15], v[26:27] op_sel_hi:[1,0]
	s_cbranch_execnz .LBB0_330

.LBB0_330:
	v_add_u32_e32 v10, 0x30c0, v97
	ds_write2_b32 v10, v24, v25 offset1:1
	v_add_u32_e32 v10, 0x30c8, v97
	ds_write2_b32 v10, v22, v23 offset1:1
	v_add_u32_e32 v10, 0x34d0, v97
	ds_write2_b32 v10, v18, v19 offset1:1
	v_add_u32_e32 v10, 0x34d8, v97
	s_and_b64 vcc, exec, s[0:1]
	ds_write2_b32 v10, v20, v21 offset1:1
	s_cbranch_vccnz .LBB0_380
	v_mov_b32_e32 v10, v114
	v_mov_b32_e32 v18, v115
	s_waitcnt vmcnt(1)
	v_pk_mul_f32 v[14:15], v[4:5], v[10:11] op_sel_hi:[1,0]
	v_pk_mul_f32 v[16:17], v[2:3], v[10:11] op_sel_hi:[1,0]
	s_waitcnt vmcnt(0)
	v_pk_mul_f32 v[12:13], v[8:9], v[18:19] op_sel_hi:[1,0]
	v_pk_mul_f32 v[10:11], v[6:7], v[18:19] op_sel_hi:[1,0]
	s_cbranch_execnz .LBB0_333

.Ls5p1_nopf:
	v_mfma_f32_32x32x16_bf16 v[82:97], v[4:7], v[154:157], 0
	v_mfma_f32_32x32x16_bf16 v[34:49], v[4:7], v[158:161], 0
	v_mfma_f32_32x32x16_bf16 v[66:81], v[4:7], v[146:149], 0
	v_mfma_f32_32x32x16_bf16 v[50:65], v[4:7], v[150:153], 0
	s_nop 8
	v_fma_f32 v4, -v201, v17, v82
	v_fma_f32 v5, v201, v2, v34
	v_fmac_f32_e32 v4, v231, v2
	v_fmac_f32_e32 v5, v231, v17
	v_fma_f32 v2, -v196, v33, v66
	v_fmac_f32_e32 v2, v200, v3
	v_fma_f32 v6, v196, v3, v50
	v_fmac_f32_e32 v6, v200, v33
	v_fma_f32 v3, -v201, v5, v83
	v_fma_f32 v7, v201, v4, v35
	v_fmac_f32_e32 v3, v231, v4
	v_fmac_f32_e32 v7, v231, v5
	v_fma_f32 v4, -v196, v6, v67
	v_fma_f32 v5, v196, v2, v51
	v_fmac_f32_e32 v4, v200, v2
	v_fmac_f32_e32 v5, v200, v6
	v_fma_f32 v2, -v201, v7, v84
	v_fma_f32 v6, v201, v3, v36
	v_fmac_f32_e32 v2, v231, v3
	v_fmac_f32_e32 v6, v231, v7
	v_fma_f32 v3, -v196, v5, v68
	v_fma_f32 v7, v196, v4, v52
	v_fmac_f32_e32 v3, v200, v4
	v_fmac_f32_e32 v7, v200, v5
	v_fma_f32 v4, -v201, v6, v85
	v_fma_f32 v5, v201, v2, v37
	v_fmac_f32_e32 v4, v231, v2
	v_fmac_f32_e32 v5, v231, v6
	v_fma_f32 v2, -v196, v7, v69
	v_fma_f32 v6, v196, v3, v53
	v_fmac_f32_e32 v2, v200, v3
	v_fmac_f32_e32 v6, v200, v7
	v_fma_f32 v3, -v201, v5, v86
	v_fma_f32 v7, v201, v4, v38
	v_fmac_f32_e32 v3, v231, v4
	v_fmac_f32_e32 v7, v231, v5
	v_fma_f32 v4, -v196, v6, v70
	v_fma_f32 v5, v196, v2, v54
	v_fmac_f32_e32 v4, v200, v2
	v_fmac_f32_e32 v5, v200, v6
	v_fma_f32 v2, -v201, v7, v87
	v_fma_f32 v6, v201, v3, v39
	v_fmac_f32_e32 v2, v231, v3
	v_fmac_f32_e32 v6, v231, v7
	v_fma_f32 v3, -v196, v5, v71
	v_fma_f32 v7, v196, v4, v55
	v_fmac_f32_e32 v3, v200, v4
	v_fmac_f32_e32 v7, v200, v5
	v_fma_f32 v4, -v201, v6, v88
	v_fma_f32 v5, v201, v2, v40
	v_fmac_f32_e32 v4, v231, v2
	v_fmac_f32_e32 v5, v231, v6
	v_fma_f32 v2, -v196, v7, v72
	v_fma_f32 v6, v196, v3, v56
	v_fmac_f32_e32 v2, v200, v3
	v_fmac_f32_e32 v6, v200, v7
	v_fma_f32 v3, -v201, v5, v89
	v_fma_f32 v7, v201, v4, v41
	v_fmac_f32_e32 v3, v231, v4
	v_fmac_f32_e32 v7, v231, v5
	v_fma_f32 v4, -v196, v6, v73
	v_fma_f32 v5, v196, v2, v57
	v_fmac_f32_e32 v4, v200, v2
	v_fmac_f32_e32 v5, v200, v6
	v_fma_f32 v2, -v201, v7, v90
	v_fma_f32 v6, v201, v3, v42
	v_fmac_f32_e32 v2, v231, v3
	v_fmac_f32_e32 v6, v231, v7
	v_fma_f32 v3, -v196, v5, v74
	v_fma_f32 v7, v196, v4, v58
	v_fmac_f32_e32 v3, v200, v4
	v_fmac_f32_e32 v7, v200, v5
	v_fma_f32 v4, -v201, v6, v91
	v_fma_f32 v5, v201, v2, v43
	v_fmac_f32_e32 v4, v231, v2
	v_fmac_f32_e32 v5, v231, v6
	v_fma_f32 v2, -v196, v7, v75
	v_fma_f32 v6, v196, v3, v59
	v_fmac_f32_e32 v2, v200, v3
	v_fmac_f32_e32 v6, v200, v7
	v_fma_f32 v3, -v201, v5, v92
	v_fma_f32 v7, v201, v4, v44
	v_fmac_f32_e32 v3, v231, v4
	v_fmac_f32_e32 v7, v231, v5
	v_fma_f32 v4, -v196, v6, v76
	v_fma_f32 v5, v196, v2, v60
	v_fmac_f32_e32 v4, v200, v2
	v_fmac_f32_e32 v5, v200, v6
	v_fma_f32 v2, -v201, v7, v93
	v_fma_f32 v6, v201, v3, v45
	v_fmac_f32_e32 v2, v231, v3
	v_fmac_f32_e32 v6, v231, v7
	v_fma_f32 v3, -v196, v5, v77
	v_fma_f32 v7, v196, v4, v61
	v_fmac_f32_e32 v3, v200, v4
	v_fmac_f32_e32 v7, v200, v5
	v_fma_f32 v4, -v201, v6, v94
	v_fma_f32 v5, v201, v2, v46
	v_fmac_f32_e32 v4, v231, v2
	v_fmac_f32_e32 v5, v231, v6
	v_fma_f32 v2, -v196, v7, v78
	v_fma_f32 v6, v196, v3, v62
	v_fmac_f32_e32 v2, v200, v3
	v_fmac_f32_e32 v6, v200, v7
	v_fma_f32 v3, -v201, v5, v95
	v_fma_f32 v7, v201, v4, v47
	v_fmac_f32_e32 v3, v231, v4
	v_fmac_f32_e32 v7, v231, v5
	v_fma_f32 v4, -v196, v6, v79
	v_fma_f32 v5, v196, v2, v63
	v_fmac_f32_e32 v4, v200, v2
	v_fmac_f32_e32 v5, v200, v6
	v_fma_f32 v2, -v201, v7, v96
	v_fma_f32 v6, v201, v3, v48
	v_fmac_f32_e32 v2, v231, v3
	v_fmac_f32_e32 v6, v231, v7
	v_fma_f32 v3, -v196, v5, v80
	v_fma_f32 v7, v196, v4, v64
	v_fmac_f32_e32 v3, v200, v4
	v_fmac_f32_e32 v7, v200, v5
	s_nop 0
	v_fma_f32 v34, -v201, v6, v97
	v_fmac_f32_e32 v49, v201, v2
	v_fma_f32 v35, -v196, v7, v81
	v_fmac_f32_e32 v65, v196, v3
	v_fmac_f32_e32 v34, v231, v2
	v_fmac_f32_e32 v49, v231, v6
	v_fmac_f32_e32 v35, v200, v3
	v_fmac_f32_e32 v65, v200, v7
	s_nop 0
	v_mfma_f32_32x32x16_bf16 v[82:97], v[18:21], v[154:157], 0
	v_mfma_f32_32x32x16_bf16 v[2:17], v[18:21], v[158:161], 0
	s_nop 10
	v_fma_f32 v36, -v201, v49, v82
	v_fmac_f32_e32 v36, v231, v34
	v_mfma_f32_32x32x16_bf16 v[66:81], v[18:21], v[146:149], 0
	v_fma_f32 v2, v201, v34, v2
	v_fmac_f32_e32 v2, v231, v49
	s_nop 0
	v_fma_f32 v3, v201, v36, v3
	v_fmac_f32_e32 v3, v231, v2
	s_nop 6
	v_fma_f32 v34, -v196, v65, v66
	v_mfma_f32_32x32x16_bf16 v[18:33], v[18:21], v[150:153], 0
	v_fmac_f32_e32 v34, v200, v35
	s_nop 10
	v_fma_f32 v18, v196, v35, v18
	v_fmac_f32_e32 v18, v200, v65
	v_fma_f32 v35, -v201, v2, v83
	v_fmac_f32_e32 v35, v231, v36
	v_fma_f32 v2, -v196, v18, v67
	v_fma_f32 v19, v196, v34, v19
	v_fmac_f32_e32 v2, v200, v34
	v_fmac_f32_e32 v19, v200, v18
	v_fma_f32 v18, -v201, v3, v84
	v_fma_f32 v4, v201, v35, v4
	v_fmac_f32_e32 v18, v231, v35
	v_fmac_f32_e32 v4, v231, v3
	v_fma_f32 v3, -v196, v19, v68
	v_fma_f32 v20, v196, v2, v20
	v_fmac_f32_e32 v3, v200, v2
	v_fmac_f32_e32 v20, v200, v19
	v_fma_f32 v2, -v201, v4, v85
	v_fma_f32 v5, v201, v18, v5
	v_fmac_f32_e32 v2, v231, v18
	v_fmac_f32_e32 v5, v231, v4
	v_fma_f32 v4, -v196, v20, v69
	v_fma_f32 v18, v196, v3, v21
	v_fmac_f32_e32 v4, v200, v3
	v_fmac_f32_e32 v18, v200, v20
	v_fma_f32 v3, -v201, v5, v86
	v_fma_f32 v6, v201, v2, v6
	v_fmac_f32_e32 v3, v231, v2
	v_fmac_f32_e32 v6, v231, v5
	v_fma_f32 v2, -v196, v18, v70
	v_fma_f32 v5, v196, v4, v22
	v_fmac_f32_e32 v2, v200, v4
	v_fmac_f32_e32 v5, v200, v18
	v_fma_f32 v4, -v201, v6, v87
	v_fma_f32 v7, v201, v3, v7
	v_fmac_f32_e32 v4, v231, v3
	v_fmac_f32_e32 v7, v231, v6
	v_fma_f32 v3, -v196, v5, v71
	v_fma_f32 v6, v196, v2, v23
	v_fmac_f32_e32 v3, v200, v2
	v_fmac_f32_e32 v6, v200, v5
	v_fma_f32 v2, -v201, v7, v88
	v_fma_f32 v5, v201, v4, v8
	v_fmac_f32_e32 v2, v231, v4
	v_fmac_f32_e32 v5, v231, v7
	v_fma_f32 v4, -v196, v6, v72
	v_fma_f32 v7, v196, v3, v24
	v_fmac_f32_e32 v4, v200, v3
	v_fmac_f32_e32 v7, v200, v6
	v_fma_f32 v3, -v201, v5, v89
	v_fma_f32 v6, v201, v2, v9
	v_fmac_f32_e32 v3, v231, v2
	v_fmac_f32_e32 v6, v231, v5
	v_fma_f32 v2, -v196, v7, v73
	v_fma_f32 v5, v196, v4, v25
	v_fmac_f32_e32 v2, v200, v4
	v_fmac_f32_e32 v5, v200, v7
	v_fma_f32 v4, -v201, v6, v90
	v_fma_f32 v7, v201, v3, v10
	v_fmac_f32_e32 v4, v231, v3
	v_fmac_f32_e32 v7, v231, v6
	v_fma_f32 v3, -v196, v5, v74
	v_fma_f32 v6, v196, v2, v26
	v_fmac_f32_e32 v3, v200, v2
	v_fmac_f32_e32 v6, v200, v5
	v_fma_f32 v2, -v201, v7, v91
	v_fma_f32 v5, v201, v4, v11
	v_fmac_f32_e32 v2, v231, v4
	v_fmac_f32_e32 v5, v231, v7
	v_fma_f32 v4, -v196, v6, v75
	v_fma_f32 v7, v196, v3, v27
	v_fmac_f32_e32 v4, v200, v3
	v_fmac_f32_e32 v7, v200, v6
	v_fma_f32 v3, -v201, v5, v92
	v_fma_f32 v6, v201, v2, v12
	v_fmac_f32_e32 v3, v231, v2
	v_fmac_f32_e32 v6, v231, v5
	v_fma_f32 v2, -v196, v7, v76
	v_fma_f32 v5, v196, v4, v28
	v_fmac_f32_e32 v2, v200, v4
	v_fmac_f32_e32 v5, v200, v7
	v_fma_f32 v4, -v201, v6, v93
	v_fma_f32 v7, v201, v3, v13
	v_fmac_f32_e32 v4, v231, v3
	v_fmac_f32_e32 v7, v231, v6
	v_fma_f32 v3, -v196, v5, v77
	v_fma_f32 v6, v196, v2, v29
	v_fmac_f32_e32 v3, v200, v2
	v_fmac_f32_e32 v6, v200, v5
	v_fma_f32 v2, -v201, v7, v94
	v_fma_f32 v5, v201, v4, v14
	v_fmac_f32_e32 v2, v231, v4
	v_fmac_f32_e32 v5, v231, v7
	v_fma_f32 v4, -v196, v6, v78
	v_fma_f32 v7, v196, v3, v30
	v_fmac_f32_e32 v4, v200, v3
	v_fmac_f32_e32 v7, v200, v6
	v_fma_f32 v3, -v201, v5, v95
	v_fma_f32 v6, v201, v2, v15
	v_fmac_f32_e32 v3, v231, v2
	v_fmac_f32_e32 v6, v231, v5
	v_fma_f32 v2, -v196, v7, v79
	v_fma_f32 v5, v196, v4, v31
	v_fmac_f32_e32 v2, v200, v4
	v_fmac_f32_e32 v5, v200, v7
	v_fma_f32 v4, -v201, v6, v96
	v_fma_f32 v7, v201, v3, v16
	v_fmac_f32_e32 v4, v231, v3
	v_fmac_f32_e32 v7, v231, v6
	v_fma_f32 v6, -v196, v5, v80
	v_fma_f32 v8, v196, v2, v32
	v_fmac_f32_e32 v6, v200, v2
	v_fmac_f32_e32 v8, v200, v5
	v_fma_f32 v2, -v201, v7, v97
	s_nop 0
	v_mfma_f32_32x32x16_bf16 v[82:97], v[102:105], v[154:157], 0
	v_fmac_f32_e32 v17, v201, v4
	v_fma_f32 v3, -v196, v8, v81
	v_fmac_f32_e32 v2, v231, v4
	v_fmac_f32_e32 v17, v231, v7
	v_fmac_f32_e32 v33, v196, v6
	v_mfma_f32_32x32x16_bf16 v[50:65], v[102:105], v[158:161], 0
	v_fmac_f32_e32 v3, v200, v6
	v_fmac_f32_e32 v33, v200, v8
	s_nop 3
	v_fma_f32 v4, -v201, v17, v82
	v_fmac_f32_e32 v4, v231, v2
	s_nop 3
	v_fma_f32 v5, v201, v2, v50
	v_mfma_f32_32x32x16_bf16 v[66:81], v[102:105], v[146:149], 0
	v_fmac_f32_e32 v5, v231, v17
	s_nop 0
	v_fma_f32 v7, v201, v4, v51
	v_fmac_f32_e32 v7, v231, v5
	s_nop 7
	v_fma_f32 v2, -v196, v33, v66
	v_mfma_f32_32x32x16_bf16 v[34:49], v[102:105], v[150:153], 0
	v_fmac_f32_e32 v2, v200, v3
	s_nop 10
	v_fma_f32 v6, v196, v3, v34
	v_fmac_f32_e32 v6, v200, v33
	v_fma_f32 v3, -v201, v5, v83
	v_fmac_f32_e32 v3, v231, v4
	v_fma_f32 v4, -v196, v6, v67
	v_fma_f32 v5, v196, v2, v35
	v_fmac_f32_e32 v4, v200, v2
	v_fmac_f32_e32 v5, v200, v6
	v_fma_f32 v2, -v201, v7, v84
	v_fma_f32 v6, v201, v3, v52
	v_fmac_f32_e32 v2, v231, v3
	v_fmac_f32_e32 v6, v231, v7
	v_fma_f32 v3, -v196, v5, v68
	v_fma_f32 v7, v196, v4, v36
	v_fmac_f32_e32 v3, v200, v4
	v_fmac_f32_e32 v7, v200, v5
	v_fma_f32 v4, -v201, v6, v85
	v_fma_f32 v5, v201, v2, v53
	v_fmac_f32_e32 v4, v231, v2
	v_fmac_f32_e32 v5, v231, v6
	v_fma_f32 v2, -v196, v7, v69
	v_fma_f32 v6, v196, v3, v37
	v_fmac_f32_e32 v2, v200, v3
	v_fmac_f32_e32 v6, v200, v7
	v_fma_f32 v3, -v201, v5, v86
	v_fma_f32 v7, v201, v4, v54
	v_fmac_f32_e32 v3, v231, v4
	v_fmac_f32_e32 v7, v231, v5
	v_fma_f32 v4, -v196, v6, v70
	v_fma_f32 v5, v196, v2, v38
	v_fmac_f32_e32 v4, v200, v2
	v_fmac_f32_e32 v5, v200, v6
	v_fma_f32 v2, -v201, v7, v87
	v_fma_f32 v6, v201, v3, v55
	v_fmac_f32_e32 v2, v231, v3
	v_fmac_f32_e32 v6, v231, v7
	v_fma_f32 v3, -v196, v5, v71
	v_fma_f32 v7, v196, v4, v39
	v_fmac_f32_e32 v3, v200, v4
	v_fmac_f32_e32 v7, v200, v5
	v_fma_f32 v4, -v201, v6, v88
	v_fma_f32 v5, v201, v2, v56
	v_fmac_f32_e32 v4, v231, v2
	v_fmac_f32_e32 v5, v231, v6
	v_fma_f32 v2, -v196, v7, v72
	v_fma_f32 v6, v196, v3, v40
	v_fmac_f32_e32 v2, v200, v3
	v_fmac_f32_e32 v6, v200, v7
	v_fma_f32 v3, -v201, v5, v89
	v_fma_f32 v7, v201, v4, v57
	v_fmac_f32_e32 v3, v231, v4
	v_fmac_f32_e32 v7, v231, v5
	v_fma_f32 v4, -v196, v6, v73
	v_fma_f32 v5, v196, v2, v41
	v_fmac_f32_e32 v4, v200, v2
	v_fmac_f32_e32 v5, v200, v6
	v_fma_f32 v2, -v201, v7, v90
	v_fma_f32 v6, v201, v3, v58
	v_fmac_f32_e32 v2, v231, v3
	v_fmac_f32_e32 v6, v231, v7
	v_fma_f32 v3, -v196, v5, v74
	v_fma_f32 v7, v196, v4, v42
	v_fmac_f32_e32 v3, v200, v4
	v_fmac_f32_e32 v7, v200, v5
	v_fma_f32 v4, -v201, v6, v91
	v_fma_f32 v5, v201, v2, v59
	v_fmac_f32_e32 v4, v231, v2
	v_fmac_f32_e32 v5, v231, v6
	v_fma_f32 v2, -v196, v7, v75
	v_fma_f32 v6, v196, v3, v43
	v_fmac_f32_e32 v2, v200, v3
	v_fmac_f32_e32 v6, v200, v7
	v_fma_f32 v3, -v201, v5, v92
	v_fma_f32 v7, v201, v4, v60
	v_fmac_f32_e32 v3, v231, v4
	v_fmac_f32_e32 v7, v231, v5
	v_fma_f32 v4, -v196, v6, v76
	v_fma_f32 v5, v196, v2, v44
	v_fmac_f32_e32 v4, v200, v2
	v_fmac_f32_e32 v5, v200, v6
	v_fma_f32 v2, -v201, v7, v93
	v_fma_f32 v6, v201, v3, v61
	v_fmac_f32_e32 v2, v231, v3
	v_fmac_f32_e32 v6, v231, v7
	v_fma_f32 v3, -v196, v5, v77
	v_fma_f32 v7, v196, v4, v45
	v_fmac_f32_e32 v3, v200, v4
	v_fmac_f32_e32 v7, v200, v5
	v_fma_f32 v4, -v201, v6, v94
	v_fma_f32 v5, v201, v2, v62
	v_fmac_f32_e32 v4, v231, v2
	v_fmac_f32_e32 v5, v231, v6
	v_fma_f32 v2, -v196, v7, v78
	v_fma_f32 v6, v196, v3, v46
	v_fmac_f32_e32 v2, v200, v3
	v_fmac_f32_e32 v6, v200, v7
	v_fma_f32 v3, -v201, v5, v95
	v_fma_f32 v7, v201, v4, v63
	v_fmac_f32_e32 v3, v231, v4
	v_fmac_f32_e32 v7, v231, v5
	v_fma_f32 v4, -v196, v6, v79
	v_fma_f32 v5, v196, v2, v47
	v_fmac_f32_e32 v4, v200, v2
	v_fmac_f32_e32 v5, v200, v6
	v_fma_f32 v2, -v201, v7, v96
	v_fma_f32 v6, v201, v3, v64
	v_fmac_f32_e32 v2, v231, v3
	v_fmac_f32_e32 v6, v231, v7
	v_fma_f32 v3, -v196, v5, v80
	v_fma_f32 v7, v196, v4, v48
	v_fmac_f32_e32 v3, v200, v4
	v_fmac_f32_e32 v7, v200, v5
	s_nop 0
	v_mfma_f32_32x32x16_bf16 v[18:33], v[98:101], v[150:153], 0
	v_fma_f32 v34, -v201, v6, v97
	v_fmac_f32_e32 v65, v201, v2
	v_fma_f32 v35, -v196, v7, v81
	v_fmac_f32_e32 v49, v196, v3
	v_fmac_f32_e32 v34, v231, v2
	v_fmac_f32_e32 v65, v231, v6
	v_fmac_f32_e32 v35, v200, v3
	v_fmac_f32_e32 v49, v200, v7
	v_mfma_f32_32x32x16_bf16 v[66:81], v[98:101], v[154:157], 0
	s_nop 2
	v_fma_f32 v18, v196, v35, v18
	v_fmac_f32_e32 v18, v200, v49
	s_nop 6
	v_fma_f32 v36, -v201, v65, v66
	v_mfma_f32_32x32x16_bf16 v[2:17], v[98:101], v[158:161], 0
	v_fmac_f32_e32 v36, v231, v34
	v_mfma_f32_32x32x16_bf16 v[82:97], v[98:101], v[146:149], 0
	s_nop 9
	v_fma_f32 v2, v201, v34, v2
	v_fmac_f32_e32 v2, v231, v65
	s_nop 0
	v_fma_f32 v3, v201, v36, v3
	v_fmac_f32_e32 v3, v231, v2
	v_fma_f32 v34, -v196, v49, v82
	v_fmac_f32_e32 v34, v200, v35
	v_fma_f32 v35, -v201, v2, v67
	v_fmac_f32_e32 v35, v231, v36
	v_fma_f32 v2, -v196, v18, v83
	v_fma_f32 v19, v196, v34, v19
	v_fmac_f32_e32 v2, v200, v34
	v_fmac_f32_e32 v19, v200, v18
	v_fma_f32 v18, -v201, v3, v68
	v_fma_f32 v4, v201, v35, v4
	v_fmac_f32_e32 v18, v231, v35
	v_fmac_f32_e32 v4, v231, v3
	v_fma_f32 v3, -v196, v19, v84
	v_fma_f32 v20, v196, v2, v20
	v_fmac_f32_e32 v3, v200, v2
	v_fmac_f32_e32 v20, v200, v19
	v_fma_f32 v2, -v201, v4, v69
	v_fma_f32 v5, v201, v18, v5
	v_fmac_f32_e32 v2, v231, v18
	v_fmac_f32_e32 v5, v231, v4
	v_fma_f32 v4, -v196, v20, v85
	v_fma_f32 v18, v196, v3, v21
	v_fmac_f32_e32 v4, v200, v3
	v_fmac_f32_e32 v18, v200, v20
	v_fma_f32 v3, -v201, v5, v70
	v_fma_f32 v6, v201, v2, v6
	v_fmac_f32_e32 v3, v231, v2
	v_fmac_f32_e32 v6, v231, v5
	v_fma_f32 v2, -v196, v18, v86
	v_fma_f32 v5, v196, v4, v22
	v_fmac_f32_e32 v2, v200, v4
	v_fmac_f32_e32 v5, v200, v18
	v_fma_f32 v4, -v201, v6, v71
	v_fma_f32 v7, v201, v3, v7
	v_fmac_f32_e32 v4, v231, v3
	v_fmac_f32_e32 v7, v231, v6
	v_fma_f32 v3, -v196, v5, v87
	v_fma_f32 v6, v196, v2, v23
	v_fmac_f32_e32 v3, v200, v2
	v_fmac_f32_e32 v6, v200, v5
	v_fma_f32 v2, -v201, v7, v72
	v_fma_f32 v5, v201, v4, v8
	v_fmac_f32_e32 v2, v231, v4
	v_fmac_f32_e32 v5, v231, v7
	v_fma_f32 v4, -v196, v6, v88
	v_fma_f32 v7, v196, v3, v24
	v_fmac_f32_e32 v4, v200, v3
	v_fmac_f32_e32 v7, v200, v6
	v_fma_f32 v3, -v201, v5, v73
	v_fma_f32 v6, v201, v2, v9
	v_fmac_f32_e32 v3, v231, v2
	v_fmac_f32_e32 v6, v231, v5
	v_fma_f32 v2, -v196, v7, v89
	v_fma_f32 v5, v196, v4, v25
	v_fmac_f32_e32 v2, v200, v4
	v_fmac_f32_e32 v5, v200, v7
	v_fma_f32 v4, -v201, v6, v74
	v_fma_f32 v7, v201, v3, v10
	v_fmac_f32_e32 v4, v231, v3
	v_fmac_f32_e32 v7, v231, v6
	v_fma_f32 v3, -v196, v5, v90
	v_fma_f32 v6, v196, v2, v26
	v_fmac_f32_e32 v3, v200, v2
	v_fmac_f32_e32 v6, v200, v5
	v_fma_f32 v2, -v201, v7, v75
	v_fma_f32 v5, v201, v4, v11
	v_fmac_f32_e32 v2, v231, v4
	v_fmac_f32_e32 v5, v231, v7
	v_fma_f32 v4, -v196, v6, v91
	v_fma_f32 v7, v196, v3, v27
	v_fmac_f32_e32 v4, v200, v3
	v_fmac_f32_e32 v7, v200, v6
	v_fma_f32 v3, -v201, v5, v76
	v_fma_f32 v6, v201, v2, v12
	v_fmac_f32_e32 v3, v231, v2
	v_fmac_f32_e32 v6, v231, v5
	v_fma_f32 v2, -v196, v7, v92
	v_fma_f32 v5, v196, v4, v28
	v_fmac_f32_e32 v2, v200, v4
	v_fmac_f32_e32 v5, v200, v7
	v_fma_f32 v4, -v201, v6, v77
	v_fma_f32 v7, v201, v3, v13
	v_fmac_f32_e32 v4, v231, v3
	v_fmac_f32_e32 v7, v231, v6
	v_fma_f32 v3, -v196, v5, v93
	v_fma_f32 v6, v196, v2, v29
	v_fmac_f32_e32 v3, v200, v2
	v_fmac_f32_e32 v6, v200, v5
	v_fma_f32 v2, -v201, v7, v78
	v_fma_f32 v5, v201, v4, v14
	v_fmac_f32_e32 v2, v231, v4
	v_fmac_f32_e32 v5, v231, v7
	v_fma_f32 v4, -v196, v6, v94
	v_fma_f32 v7, v196, v3, v30
	v_fmac_f32_e32 v4, v200, v3
	v_fmac_f32_e32 v7, v200, v6
	v_fma_f32 v3, -v201, v5, v79
	v_fma_f32 v6, v201, v2, v15
	v_fmac_f32_e32 v3, v231, v2
	v_fmac_f32_e32 v6, v231, v5
	v_fma_f32 v2, -v196, v7, v95
	v_fma_f32 v5, v196, v4, v31
	v_fmac_f32_e32 v2, v200, v4
	v_fmac_f32_e32 v5, v200, v7
	v_fma_f32 v7, v201, v3, v16
	v_fma_f32 v4, -v201, v6, v80
	v_fmac_f32_e32 v7, v231, v6
	v_fma_f32 v6, -v196, v5, v96
	v_fma_f32 v8, v196, v2, v32
	v_fmac_f32_e32 v4, v231, v3
	v_fmac_f32_e32 v6, v200, v2
	v_fmac_f32_e32 v8, v200, v5
	s_nop 0
	v_fma_f32 v2, -v201, v7, v81
	v_fmac_f32_e32 v17, v201, v4
	v_fma_f32 v3, -v196, v8, v97
	v_fmac_f32_e32 v33, v196, v6
	v_fmac_f32_e32 v2, v231, v4
	v_fmac_f32_e32 v17, v231, v7
	v_fmac_f32_e32 v3, v200, v6
	v_fmac_f32_e32 v33, v200, v8
	s_cbranch_scc0 .LBB0_664
	v_or_b32_e32 v10, s22, v206
	v_ashrrev_i32_e32 v11, 31, v10
	s_and_b64 vcc, exec, s[34:35]
	ds_write2st64_b32 v199, v2, v17 offset1:1
	ds_write2st64_b32 v199, v3, v33 offset0:2 offset1:3
	s_cbranch_vccz .LBB0_667
	v_lshlrev_b64 v[2:3], 8, v[10:11]
	v_lshl_add_u64 v[4:5], v[184:185], 0, v[2:3]
	v_lshl_add_u64 v[6:7], v[186:187], 0, v[2:3]
	global_load_dwordx4 v[36:39], v[4:5], off offset:16
	global_load_dwordx4 v[40:43], v[4:5], off
	global_load_dwordx4 v[44:47], v[4:5], off offset:80
	global_load_dwordx4 v[48:51], v[4:5], off offset:64
	global_load_dwordx4 v[52:55], v[4:5], off offset:144
	global_load_dwordx4 v[56:59], v[4:5], off offset:128
	global_load_dwordx4 v[60:63], v[4:5], off offset:208
	global_load_dwordx4 v[64:67], v[4:5], off offset:192
	global_load_dwordx4 v[68:71], v[6:7], off offset:16
	global_load_dwordx4 v[72:75], v[6:7], off
	global_load_dwordx4 v[76:79], v[6:7], off offset:80
	global_load_dwordx4 v[80:83], v[6:7], off offset:64
	global_load_dwordx4 v[84:87], v[6:7], off offset:144
	global_load_dwordx4 v[88:91], v[6:7], off offset:128
	global_load_dwordx4 v[92:95], v[6:7], off offset:208
	global_load_dwordx4 v[96:99], v[6:7], off offset:192
	s_waitcnt vmcnt(14)
	v_pk_mul_f32 v[36:37], v[180:181], v[36:37]
	v_pk_mul_f32 v[38:39], v[180:181], v[38:39]
	v_pk_mul_f32 v[40:41], v[180:181], v[40:41]
	v_pk_mul_f32 v[42:43], v[180:181], v[42:43]
	v_bfe_u32 v16, v40, 16, 1
	v_bfe_u32 v17, v41, 16, 1
	v_bfe_u32 v18, v42, 16, 1
	v_bfe_u32 v19, v43, 16, 1
	v_bfe_u32 v20, v36, 16, 1
	v_bfe_u32 v21, v37, 16, 1
	v_bfe_u32 v22, v38, 16, 1
	v_bfe_u32 v23, v39, 16, 1
	v_add3_u32 v40, v40, v16, s75
	v_add3_u32 v41, v41, v17, s75
	v_add3_u32 v42, v42, v18, s75
	v_add3_u32 v43, v43, v19, s75
	v_add3_u32 v36, v36, v20, s75
	v_add3_u32 v37, v37, v21, s75
	v_add3_u32 v38, v38, v22, s75
	v_add3_u32 v39, v39, v23, s75
	v_perm_b32 v12, v41, v40, s76
	v_perm_b32 v13, v43, v42, s76
	v_perm_b32 v14, v37, v36, s76
	v_perm_b32 v15, v39, v38, s76
	ds_write_b128 v207, v[12:15]
	s_waitcnt vmcnt(12)
	v_pk_mul_f32 v[44:45], v[180:181], v[44:45]
	v_pk_mul_f32 v[46:47], v[180:181], v[46:47]
	v_pk_mul_f32 v[48:49], v[180:181], v[48:49]
	v_pk_mul_f32 v[50:51], v[180:181], v[50:51]
	v_bfe_u32 v16, v48, 16, 1
	v_bfe_u32 v17, v49, 16, 1
	v_bfe_u32 v18, v50, 16, 1
	v_bfe_u32 v19, v51, 16, 1
	v_bfe_u32 v20, v44, 16, 1
	v_bfe_u32 v21, v45, 16, 1
	v_bfe_u32 v22, v46, 16, 1
	v_bfe_u32 v23, v47, 16, 1
	v_add3_u32 v48, v48, v16, s75
	v_add3_u32 v49, v49, v17, s75
	v_add3_u32 v50, v50, v18, s75
	v_add3_u32 v51, v51, v19, s75
	v_add3_u32 v44, v44, v20, s75
	v_add3_u32 v45, v45, v21, s75
	v_add3_u32 v46, v46, v22, s75
	v_add3_u32 v47, v47, v23, s75
	v_perm_b32 v24, v49, v48, s76
	v_perm_b32 v25, v51, v50, s76
	v_perm_b32 v26, v45, v44, s76
	v_perm_b32 v27, v47, v46, s76
	ds_write_b128 v208, v[24:27]
	s_waitcnt vmcnt(10)
	v_pk_mul_f32 v[52:53], v[180:181], v[52:53]
	v_pk_mul_f32 v[54:55], v[180:181], v[54:55]
	v_pk_mul_f32 v[56:57], v[180:181], v[56:57]
	v_pk_mul_f32 v[58:59], v[180:181], v[58:59]
	v_bfe_u32 v16, v56, 16, 1
	v_bfe_u32 v17, v57, 16, 1
	v_bfe_u32 v18, v58, 16, 1
	v_bfe_u32 v19, v59, 16, 1
	v_bfe_u32 v20, v52, 16, 1
	v_bfe_u32 v21, v53, 16, 1
	v_bfe_u32 v22, v54, 16, 1
	v_bfe_u32 v23, v55, 16, 1
	v_add3_u32 v56, v56, v16, s75
	v_add3_u32 v57, v57, v17, s75
	v_add3_u32 v58, v58, v18, s75
	v_add3_u32 v59, v59, v19, s75
	v_add3_u32 v52, v52, v20, s75
	v_add3_u32 v53, v53, v21, s75
	v_add3_u32 v54, v54, v22, s75
	v_add3_u32 v55, v55, v23, s75
	v_perm_b32 v12, v57, v56, s76
	v_perm_b32 v13, v59, v58, s76
	v_perm_b32 v14, v53, v52, s76
	v_perm_b32 v15, v55, v54, s76
	ds_write_b128 v209, v[12:15]
	s_waitcnt vmcnt(8)
	v_pk_mul_f32 v[60:61], v[180:181], v[60:61]
	v_pk_mul_f32 v[62:63], v[180:181], v[62:63]
	v_pk_mul_f32 v[64:65], v[180:181], v[64:65]
	v_pk_mul_f32 v[66:67], v[180:181], v[66:67]
	v_bfe_u32 v16, v64, 16, 1
	v_bfe_u32 v17, v65, 16, 1
	v_bfe_u32 v18, v66, 16, 1
	v_bfe_u32 v19, v67, 16, 1
	v_bfe_u32 v20, v60, 16, 1
	v_bfe_u32 v21, v61, 16, 1
	v_bfe_u32 v22, v62, 16, 1
	v_bfe_u32 v23, v63, 16, 1
	v_add3_u32 v64, v64, v16, s75
	v_add3_u32 v65, v65, v17, s75
	v_add3_u32 v66, v66, v18, s75
	v_add3_u32 v67, v67, v19, s75
	v_add3_u32 v60, v60, v20, s75
	v_add3_u32 v61, v61, v21, s75
	v_add3_u32 v62, v62, v22, s75
	v_add3_u32 v63, v63, v23, s75
	v_perm_b32 v24, v65, v64, s76
	v_perm_b32 v25, v67, v66, s76
	v_perm_b32 v26, v61, v60, s76
	v_perm_b32 v27, v63, v62, s76
	ds_write_b128 v210, v[24:27]
	s_waitcnt vmcnt(6)
	v_pk_mul_f32 v[68:69], v[68:69], v[182:183]
	v_pk_mul_f32 v[70:71], v[70:71], v[182:183]
	v_pk_mul_f32 v[72:73], v[72:73], v[182:183]
	v_pk_mul_f32 v[74:75], v[74:75], v[182:183]
	v_bfe_u32 v16, v72, 16, 1
	v_bfe_u32 v17, v73, 16, 1
	v_bfe_u32 v18, v74, 16, 1
	v_bfe_u32 v19, v75, 16, 1
	v_bfe_u32 v20, v68, 16, 1
	v_bfe_u32 v21, v69, 16, 1
	v_bfe_u32 v22, v70, 16, 1
	v_bfe_u32 v23, v71, 16, 1
	v_add3_u32 v72, v72, v16, s75
	v_add3_u32 v73, v73, v17, s75
	v_add3_u32 v74, v74, v18, s75
	v_add3_u32 v75, v75, v19, s75
	v_add3_u32 v68, v68, v20, s75
	v_add3_u32 v69, v69, v21, s75
	v_add3_u32 v70, v70, v22, s75
	v_add3_u32 v71, v71, v23, s75
	v_perm_b32 v12, v73, v72, s76
	v_perm_b32 v13, v75, v74, s76
	v_perm_b32 v14, v69, v68, s76
	v_perm_b32 v15, v71, v70, s76
	ds_write_b128 v211, v[12:15]
	s_waitcnt vmcnt(4)
	v_pk_mul_f32 v[76:77], v[76:77], v[182:183]
	v_pk_mul_f32 v[78:79], v[78:79], v[182:183]
	v_pk_mul_f32 v[80:81], v[80:81], v[182:183]
	v_pk_mul_f32 v[82:83], v[82:83], v[182:183]
	v_bfe_u32 v16, v80, 16, 1
	v_bfe_u32 v17, v81, 16, 1
	v_bfe_u32 v18, v82, 16, 1
	v_bfe_u32 v19, v83, 16, 1
	v_bfe_u32 v20, v76, 16, 1
	v_bfe_u32 v21, v77, 16, 1
	v_bfe_u32 v22, v78, 16, 1
	v_bfe_u32 v23, v79, 16, 1
	v_add3_u32 v80, v80, v16, s75
	v_add3_u32 v81, v81, v17, s75
	v_add3_u32 v82, v82, v18, s75
	v_add3_u32 v83, v83, v19, s75
	v_add3_u32 v76, v76, v20, s75
	v_add3_u32 v77, v77, v21, s75
	v_add3_u32 v78, v78, v22, s75
	v_add3_u32 v79, v79, v23, s75
	v_perm_b32 v24, v81, v80, s76
	v_perm_b32 v25, v83, v82, s76
	v_perm_b32 v26, v77, v76, s76
	v_perm_b32 v27, v79, v78, s76
	ds_write_b128 v212, v[24:27]
	s_waitcnt vmcnt(2)
	v_pk_mul_f32 v[84:85], v[84:85], v[182:183]
	v_pk_mul_f32 v[86:87], v[86:87], v[182:183]
	v_pk_mul_f32 v[88:89], v[88:89], v[182:183]
	v_pk_mul_f32 v[90:91], v[90:91], v[182:183]
	v_bfe_u32 v16, v88, 16, 1
	v_bfe_u32 v17, v89, 16, 1
	v_bfe_u32 v18, v90, 16, 1
	v_bfe_u32 v19, v91, 16, 1
	v_bfe_u32 v20, v84, 16, 1
	v_bfe_u32 v21, v85, 16, 1
	v_bfe_u32 v22, v86, 16, 1
	v_bfe_u32 v23, v87, 16, 1
	v_add3_u32 v88, v88, v16, s75
	v_add3_u32 v89, v89, v17, s75
	v_add3_u32 v90, v90, v18, s75
	v_add3_u32 v91, v91, v19, s75
	v_add3_u32 v84, v84, v20, s75
	v_add3_u32 v85, v85, v21, s75
	v_add3_u32 v86, v86, v22, s75
	v_add3_u32 v87, v87, v23, s75
	v_perm_b32 v12, v89, v88, s76
	v_perm_b32 v13, v91, v90, s76
	v_perm_b32 v14, v85, v84, s76
	v_perm_b32 v15, v87, v86, s76
	ds_write_b128 v213, v[12:15]
	s_waitcnt vmcnt(0)
	v_pk_mul_f32 v[92:93], v[92:93], v[182:183]
	v_pk_mul_f32 v[94:95], v[94:95], v[182:183]
	v_pk_mul_f32 v[96:97], v[96:97], v[182:183]
	v_pk_mul_f32 v[98:99], v[98:99], v[182:183]
	v_bfe_u32 v16, v96, 16, 1
	v_bfe_u32 v17, v97, 16, 1
	v_bfe_u32 v18, v98, 16, 1
	v_bfe_u32 v19, v99, 16, 1
	v_bfe_u32 v20, v92, 16, 1
	v_bfe_u32 v21, v93, 16, 1
	v_bfe_u32 v22, v94, 16, 1
	v_bfe_u32 v23, v95, 16, 1
	v_add3_u32 v96, v96, v16, s75
	v_add3_u32 v97, v97, v17, s75
	v_add3_u32 v98, v98, v18, s75
	v_add3_u32 v99, v99, v19, s75
	v_add3_u32 v92, v92, v20, s75
	v_add3_u32 v93, v93, v21, s75
	v_add3_u32 v94, v94, v22, s75
	v_add3_u32 v95, v95, v23, s75
	v_perm_b32 v24, v97, v96, s76
	v_perm_b32 v25, v99, v98, s76
	v_perm_b32 v26, v93, v92, s76
	v_perm_b32 v27, v95, v94, s76
	ds_write_b128 v214, v[24:27]
